# softmax row-max as v_max3 chain (drop redundant canonicalising v_max) in A and C attention tiles
# speedup vs baseline: 1.0161x; 1.0161x over previous
.LBB0_168:
	v_mul_f32_e32 v76, 0x3fb8aa3b, v49
	v_mul_f32_e32 v77, 0x3fb8aa3b, v48
	v_mul_f32_e32 v75, 0x3fb8aa3b, v50
	v_mul_f32_e32 v74, 0x3fb8aa3b, v51
	v_mul_f32_e32 v73, 0x3fb8aa3b, v52
	v_mul_f32_e32 v71, 0x3fb8aa3b, v53
	v_mul_f32_e32 v69, 0x3fb8aa3b, v54
	v_mul_f32_e32 v67, 0x3fb8aa3b, v55
	v_mul_f32_e32 v66, 0x3fb8aa3b, v56
	v_mul_f32_e32 v68, 0x3fb8aa3b, v57
	v_mul_f32_e32 v70, 0x3fb8aa3b, v58
	v_mul_f32_e32 v72, 0x3fb8aa3b, v59
	v_mul_f32_e32 v51, 0x3fb8aa3b, v60
	v_mul_f32_e32 v50, 0x3fb8aa3b, v61
	v_mul_f32_e32 v49, 0x3fb8aa3b, v62
	v_mul_f32_e32 v48, 0x3fb8aa3b, v63
	v_max3_f32 v0, v65, v76, v14
	v_max3_f32 v0, v0, v15, v77
	v_max3_f32 v0, v0, v64, v75
	v_max3_f32 v0, v0, v74, v12
	v_max3_f32 v0, v0, v13, v73
	v_max3_f32 v0, v0, v71, v10
	v_max3_f32 v0, v0, v11, v69
	v_max3_f32 v0, v0, v67, v8
	v_max3_f32 v0, v0, v9, v66
	v_max3_f32 v0, v0, v68, v6
	v_max3_f32 v0, v0, v7, v70
	v_max3_f32 v0, v0, v72, v4
	v_max3_f32 v0, v0, v5, v51
	v_max3_f32 v0, v0, v50, v2
	v_max3_f32 v0, v0, v3, v49
	v_max3_f32 v0, v0, v48, v48
	v_and_b32_e32 v53, 64, v199
	v_xor_b32_e32 v52, 32, v199
	v_add_u32_e32 v53, 64, v53
	v_cmp_lt_i32_e32 vcc, v52, v53
	s_nop 1
	v_cndmask_b32_e32 v52, v199, v52, vcc
	v_lshlrev_b32_e32 v52, 2, v52
	ds_bpermute_b32 v52, v52, v0
	s_waitcnt lgkmcnt(0)
	v_max3_f32 v52, v118, v0, v52
	v_sub_f32_e32 v0, v118, v52
	v_exp_f32_e32 v0, v0
	s_nop 0
	v_cmp_eq_f32_e32 vcc, 1.0, v0
	s_cmp_eq_u64 vcc, exec
	s_cbranch_scc1 .LBB0_170
	v_pk_mul_f32 v[46:47], v[46:47], v[0:1] op_sel_hi:[1,0]
	v_pk_mul_f32 v[44:45], v[44:45], v[0:1] op_sel_hi:[1,0]
	v_pk_mul_f32 v[42:43], v[42:43], v[0:1] op_sel_hi:[1,0]
	v_pk_mul_f32 v[40:41], v[40:41], v[0:1] op_sel_hi:[1,0]
	v_pk_mul_f32 v[38:39], v[38:39], v[0:1] op_sel_hi:[1,0]
	v_pk_mul_f32 v[36:37], v[36:37], v[0:1] op_sel_hi:[1,0]
	v_pk_mul_f32 v[34:35], v[34:35], v[0:1] op_sel_hi:[1,0]
	v_pk_mul_f32 v[32:33], v[32:33], v[0:1] op_sel_hi:[1,0]
	v_pk_mul_f32 v[30:31], v[30:31], v[0:1] op_sel_hi:[1,0]
	v_pk_mul_f32 v[28:29], v[28:29], v[0:1] op_sel_hi:[1,0]
	v_pk_mul_f32 v[26:27], v[26:27], v[0:1] op_sel_hi:[1,0]
	v_pk_mul_f32 v[24:25], v[24:25], v[0:1] op_sel_hi:[1,0]
	v_pk_mul_f32 v[22:23], v[22:23], v[0:1] op_sel_hi:[1,0]
	v_pk_mul_f32 v[20:21], v[20:21], v[0:1] op_sel_hi:[1,0]
	v_pk_mul_f32 v[18:19], v[18:19], v[0:1] op_sel_hi:[1,0]
	v_pk_mul_f32 v[16:17], v[16:17], v[0:1] op_sel_hi:[1,0]

.LBB0_726:
	v_max3_f32 v0, v37, v35, v40
	v_max3_f32 v0, v0, v38, v41
	v_max3_f32 v0, v0, v39, v34
	v_max3_f32 v0, v0, v36, v44
	v_max3_f32 v0, v0, v42, v45
	v_max3_f32 v0, v0, v43, v48
	v_max3_f32 v0, v0, v46, v49
	v_max3_f32 v0, v0, v47, v52
	v_max3_f32 v0, v0, v50, v53
	v_max3_f32 v0, v0, v51, v60
	v_max3_f32 v0, v0, v54, v61
	v_max3_f32 v0, v0, v55, v58
	v_max3_f32 v0, v0, v56, v59
	v_max3_f32 v0, v0, v57, v64
	v_max3_f32 v0, v0, v62, v65
	v_max3_f32 v0, v0, v63, v63
	v_and_b32_e32 v3, 64, v199
	v_xor_b32_e32 v2, 32, v199
	v_add_u32_e32 v3, 64, v3
	v_cmp_lt_i32_e32 vcc, v2, v3
	s_mov_b32 s18, 0xff800000
	s_nop 0
	v_cndmask_b32_e32 v2, v199, v2, vcc
	v_lshlrev_b32_e32 v2, 2, v2
	ds_bpermute_b32 v2, v2, v0
	s_waitcnt lgkmcnt(0)
	v_max3_f32 v225, v0, v2, s18
	v_sub_f32_e32 v3, v38, v225
	v_exp_f32_e32 v67, v3
	v_sub_f32_e32 v3, v40, v225
	v_exp_f32_e32 v73, v3
	v_sub_f32_e32 v3, v39, v225
	v_exp_f32_e32 v66, v3
	v_sub_f32_e32 v3, v41, v225
	v_exp_f32_e32 v72, v3
	v_sub_f32_e32 v3, v42, v225
	v_exp_f32_e32 v69, v3
	v_sub_f32_e32 v3, v44, v225
	v_exp_f32_e32 v75, v3
	v_sub_f32_e32 v3, v43, v225
	v_exp_f32_e32 v68, v3
	v_sub_f32_e32 v3, v45, v225
	v_exp_f32_e32 v74, v3
	v_sub_f32_e32 v3, v46, v225
	v_exp_f32_e32 v77, v3
	v_sub_f32_e32 v3, v48, v225
	v_sub_f32_e32 v2, 0xff800000, v225
	v_exp_f32_e32 v177, v3
	v_sub_f32_e32 v3, v47, v225
	v_exp_f32_e32 v70, v3
	v_sub_f32_e32 v3, v49, v225
	v_exp_f32_e32 v178, v2
	v_exp_f32_e32 v76, v3
	v_sub_f32_e32 v3, v50, v225
	v_exp_f32_e32 v79, v3
	v_sub_f32_e32 v3, v52, v225
	v_exp_f32_e32 v179, v3
	v_sub_f32_e32 v3, v51, v225
	v_exp_f32_e32 v52, v3
	v_sub_f32_e32 v3, v53, v225
	v_cmp_eq_f32_e32 vcc, 1.0, v178
	v_exp_f32_e32 v78, v3
	v_sub_f32_e32 v3, v54, v225
	v_sub_f32_e32 v2, v56, v225
	s_cmp_lg_u64 vcc, exec
	v_sub_f32_e32 v0, v34, v225
	v_exp_f32_e32 v151, v3
	v_sub_f32_e32 v3, v60, v225
	v_exp_f32_e32 v181, v2
	v_mul_f32_e32 v2, 0, v178
	s_cselect_b64 vcc, -1, 0
	v_exp_f32_e32 v15, v0
	v_sub_f32_e32 v0, v36, v225
	v_exp_f32_e32 v180, v3
	v_sub_f32_e32 v3, v55, v225
	v_cndmask_b32_e32 v16, 0, v2, vcc
	v_exp_f32_e32 v71, v0
	v_sub_f32_e32 v0, v35, v225
	v_exp_f32_e32 v54, v3
	v_sub_f32_e32 v3, v61, v225
	v_mov_b32_e32 v17, v16
	v_mov_b32_e32 v18, v16
	v_mov_b32_e32 v19, v16
	v_mov_b32_e32 v20, v16
	v_mov_b32_e32 v21, v16
	v_mov_b32_e32 v22, v16
	v_mov_b32_e32 v23, v16
	v_mov_b32_e32 v24, v16
	v_mov_b32_e32 v25, v16
	v_mov_b32_e32 v26, v16
	v_mov_b32_e32 v27, v16
	v_mov_b32_e32 v28, v16
	v_mov_b32_e32 v29, v16
	v_mov_b32_e32 v30, v16
	v_mov_b32_e32 v31, v16
	v_exp_f32_e32 v14, v0
	v_sub_f32_e32 v0, v37, v225
	v_exp_f32_e32 v60, v3
	ds_read_b64_tr_b16 v[232:233], v205 offset:0
	ds_read_b64_tr_b16 v[234:235], v205 offset:1536
	ds_read_b64_tr_b16 v[228:229], v205 offset:64
	ds_read_b64_tr_b16 v[230:231], v205 offset:1600
	ds_read_b64_tr_b16 v[188:189], v205 offset:3072
	ds_read_b64_tr_b16 v[190:191], v205 offset:4608
	ds_read_b64_tr_b16 v[184:185], v205 offset:3136
	ds_read_b64_tr_b16 v[186:187], v205 offset:4672
	ds_read_b64_tr_b16 v[48:49], v205 offset:6144
	ds_read_b64_tr_b16 v[50:51], v205 offset:7680
	ds_read_b64_tr_b16 v[10:11], v205 offset:6208
	ds_read_b64_tr_b16 v[12:13], v205 offset:7744
	ds_read_b64_tr_b16 v[6:7], v205 offset:9216
	ds_read_b64_tr_b16 v[8:9], v205 offset:10752
	ds_read_b64_tr_b16 v[2:3], v205 offset:9280
	ds_read_b64_tr_b16 v[4:5], v205 offset:10816
	s_waitcnt lgkmcnt(0)
	v_cvt_pk_bf16_f32 v236, v15, v14
	v_cvt_pk_bf16_f32 v237, v67, v66
	v_cvt_pk_bf16_f32 v238, v69, v68
	v_cvt_pk_bf16_f32 v239, v77, v70
	v_sub_f32_e32 v53, v58, v225
	v_mfma_f32_32x32x16_bf16 v[32:47], v[232:235], v[236:239], v[16:31]
	v_exp_f32_e32 v182, v53
	v_sub_f32_e32 v53, v57, v225
	v_exp_f32_e32 v56, v53
	v_sub_f32_e32 v53, v59, v225
	v_exp_f32_e32 v176, v53
	v_sub_f32_e32 v53, v62, v225
	v_exp_f32_e32 v59, v53
	v_mfma_f32_32x32x16_bf16 v[16:31], v[228:231], v[236:239], v[16:31]
	v_sub_f32_e32 v53, v63, v225
	v_exp_f32_e32 v58, v53
	v_cvt_pk_bf16_f32 v228, v79, v52
	v_cvt_pk_bf16_f32 v229, v151, v54
	v_cvt_pk_bf16_f32 v230, v181, v56
	v_cvt_pk_bf16_f32 v231, v59, v58
	v_sub_f32_e32 v53, v64, v225
	v_mfma_f32_32x32x16_bf16 v[32:47], v[188:191], v[228:231], v[32:47]
	v_exp_f32_e32 v63, v53
	v_sub_f32_e32 v53, v65, v225
	v_exp_f32_e32 v0, v0
	v_exp_f32_e32 v62, v53
	s_andn2_b64 vcc, exec, s[16:17]
	v_mfma_f32_32x32x16_bf16 v[16:31], v[184:187], v[228:231], v[16:31]
	s_cbranch_vccnz .LBB0_728
	v_cvt_pk_bf16_f32 v184, v71, v0
	v_cvt_pk_bf16_f32 v185, v73, v72
	v_cvt_pk_bf16_f32 v186, v75, v74
	v_cvt_pk_bf16_f32 v187, v177, v76
	s_nop 0
	v_mfma_f32_32x32x16_bf16 v[32:47], v[48:51], v[184:187], v[32:47]
	v_mfma_f32_32x32x16_bf16 v[16:31], v[10:13], v[184:187], v[16:31]
	v_cvt_pk_bf16_f32 v10, v179, v78
	v_cvt_pk_bf16_f32 v11, v180, v60
	v_cvt_pk_bf16_f32 v12, v182, v176
	v_cvt_pk_bf16_f32 v13, v63, v62
	s_nop 0
	v_mfma_f32_32x32x16_bf16 v[32:47], v[6:9], v[10:13], v[32:47]
	v_mfma_f32_32x32x16_bf16 v[16:31], v[2:5], v[10:13], v[16:31]

.LBB0_746:
	v_max3_f32 v0, v5, v3, v8
	v_max3_f32 v0, v0, v6, v9
	v_max3_f32 v0, v0, v7, v2
	v_max3_f32 v0, v0, v4, v12
	v_max3_f32 v0, v0, v10, v13
	v_max3_f32 v0, v0, v11, v176
	v_max3_f32 v0, v0, v14, v177
	v_max3_f32 v0, v0, v15, v180
	v_max3_f32 v0, v0, v178, v181
	v_max3_f32 v0, v0, v179, v184
	v_max3_f32 v0, v0, v182, v185
	v_max3_f32 v0, v0, v183, v188
	v_max3_f32 v0, v0, v186, v189
	v_max3_f32 v0, v0, v187, v192
	v_max3_f32 v0, v0, v190, v193
	v_max3_f32 v0, v0, v191, v191
	v_and_b32_e32 v49, 64, v199
	v_xor_b32_e32 v48, 32, v199
	v_add_u32_e32 v49, 64, v49
	v_cmp_lt_i32_e32 vcc, v48, v49
	s_nop 1
	v_cndmask_b32_e32 v48, v199, v48, vcc
	v_lshlrev_b32_e32 v48, 2, v48
	ds_bpermute_b32 v48, v48, v0
	s_waitcnt lgkmcnt(0)
	v_max3_f32 v52, v225, v0, v48
	v_sub_f32_e32 v0, v225, v52
	v_exp_f32_e32 v0, v0
	s_nop 0
	v_cmp_eq_f32_e32 vcc, 1.0, v0
	s_cmp_eq_u64 vcc, exec
	s_cbranch_scc1 .LBB0_748
	v_pk_mul_f32 v[46:47], v[46:47], v[0:1] op_sel_hi:[1,0]
	v_pk_mul_f32 v[44:45], v[44:45], v[0:1] op_sel_hi:[1,0]
	v_pk_mul_f32 v[42:43], v[42:43], v[0:1] op_sel_hi:[1,0]
	v_pk_mul_f32 v[40:41], v[40:41], v[0:1] op_sel_hi:[1,0]
	v_pk_mul_f32 v[38:39], v[38:39], v[0:1] op_sel_hi:[1,0]
	v_pk_mul_f32 v[36:37], v[36:37], v[0:1] op_sel_hi:[1,0]
	v_pk_mul_f32 v[34:35], v[34:35], v[0:1] op_sel_hi:[1,0]
	v_pk_mul_f32 v[32:33], v[32:33], v[0:1] op_sel_hi:[1,0]
	v_pk_mul_f32 v[30:31], v[30:31], v[0:1] op_sel_hi:[1,0]
	v_pk_mul_f32 v[28:29], v[28:29], v[0:1] op_sel_hi:[1,0]
	v_pk_mul_f32 v[26:27], v[26:27], v[0:1] op_sel_hi:[1,0]
	v_pk_mul_f32 v[24:25], v[24:25], v[0:1] op_sel_hi:[1,0]
	v_pk_mul_f32 v[22:23], v[22:23], v[0:1] op_sel_hi:[1,0]
	v_pk_mul_f32 v[20:21], v[20:21], v[0:1] op_sel_hi:[1,0]
	v_pk_mul_f32 v[18:19], v[18:19], v[0:1] op_sel_hi:[1,0]
	v_pk_mul_f32 v[16:17], v[16:17], v[0:1] op_sel_hi:[1,0]
